# first grid barrier: cache invalidate issued at arrival too
# baseline (speedup 1.0000x reference)
.LBB0_212:
	s_mov_b64 s[10:11], exec
	s_lshl_b32 s6, s3, 8
	s_getpc_b64 s[8:9]
	s_add_u32 s8, s8, g_ctl@rel32@lo+4
	s_addc_u32 s9, s9, g_ctl@rel32@hi+12
	v_mbcnt_lo_u32_b32 v1, s10, 0
	s_add_u32 s8, s8, s6
	v_mbcnt_hi_u32_b32 v1, s11, v1
	s_mov_b32 s7, 0
	s_addc_u32 s9, s9, 0
	v_cmp_eq_u32_e32 vcc, 0, v1
	buffer_inv sc1
	s_and_saveexec_b64 s[12:13], vcc
	s_cbranch_execz .LBB0_214
	s_bcnt1_i32_b64 s6, s[10:11]
	v_mov_b32_e32 v3, 0x1000
	v_mov_b32_e32 v4, s6
	global_atomic_add v3, v3, v4, s[8:9] offset:1024 sc0

.LBB0_227:
	s_or_b64 exec, exec, s[12:13]
	s_waitcnt vmcnt(0)
	s_waitcnt vmcnt(0)

.LBB0_245:
	s_or_b64 exec, exec, s[12:13]
	s_mov_b64 s[12:13], exec
	v_mbcnt_lo_u32_b32 v0, s12, 0
	v_mbcnt_hi_u32_b32 v0, s13, v0
	v_cmp_eq_u32_e32 vcc, 0, v0
	s_waitcnt vmcnt(0)
	s_and_saveexec_b64 s[14:15], vcc
	s_cbranch_execz .LBB0_247
	s_bcnt1_i32_b64 s12, s[12:13]
	v_mov_b32_e32 v0, 0x2000
	v_mov_b32_e32 v1, s12
	global_atomic_add v0, v1, s[8:9] offset:1024
